# row passes: all eight o-row loads issued up front into distinct registers (was 4-5 dependent round trips), on top of state-walk LDS staging and attention reference-in-SrcC
# speedup vs baseline: 1.0125x; 1.0048x over previous
; __device__ __forceinline__ void row_pass(const RowPass& rp) {
;     ...
;         const int v = (row < MLAT) ? (row >> 12) : 2;
;         const float* xs = (row < MLAT) ? rp.src_lat + (size_t)row * D : rp.src_ctx + (size_t)(row - MLAT) * D;
;         f32x4 x[8];
; #pragma unroll
;         for (int j = 0; j < 8; ++j) x[j] = *(const f32x4*)(xs + 4 * (lane + 64 * j));
;         if (rp.o) {
;             const bf16_t* orow = rp.o + (size_t)row * D; f32x4 ov[8]; float ss = 0.f;
; #pragma unroll
;             for (int j = 0; j < 8; ++j) { const u32x2 w2 = *(const u32x2*)(orow + 4 * (lane + 64 * j));
;                 ov[j] = (f32x4){__uint_as_float(w2.x << 16), __uint_as_float(w2.x & 0xffff0000u), __uint_as_float(w2.y << 16), __uint_as_float(w2.y & 0xffff0000u)};
;                 ss += ov[j][0] * ov[j][0] + ov[j][1] * ov[j][1] + ov[j][2] * ov[j][2] + ov[j][3] * ov[j][3]; }
;             const float rstd = rsqrtf(wave_sum(ss) * (1.f / D) + EPS);
.LBB0_902:
	v_min_i32_e32 v2, 0x2000, v42
	v_cmp_gt_i32_e64 s[0:1], s70, v42
	v_ashrrev_i32_e32 v106, 12, v2
	v_add_u32_e32 v2, 0xffffe000, v42
	v_mov_b32_e32 v4, s9
	v_mov_b32_e32 v5, s4
	v_cndmask_b32_e64 v3, 0, v43, s[0:1]
	v_cndmask_b32_e64 v2, v2, v42, s[0:1]
	v_cndmask_b32_e64 v5, v4, v5, s[0:1]
	v_mov_b32_e32 v4, s20
	v_mov_b32_e32 v6, s5
	v_cndmask_b32_e64 v4, v4, v6, s[0:1]
	v_lshlrev_b64 v[74:75], 13, v[2:3]
	s_mov_b32 s21, 0xd400000
	v_lshl_add_u64 v[2:3], v[4:5], 0, v[74:75]
	v_add_co_u32_e32 v34, vcc, s21, v64
	v_lshl_add_u64 v[4:5], v[2:3], 0, v[0:1]
	s_nop 0
	v_addc_co_u32_e32 v35, vcc, 0, v65, vcc
	global_load_dwordx4 v[6:9], v[4:5], off
	global_load_dwordx4 v[18:21], v[4:5], off offset:1024
	global_load_dwordx4 v[22:25], v[4:5], off offset:2048
	global_load_dwordx4 v[26:29], v[4:5], off offset:3072
	global_load_dwordx2 v[36:37], v[34:35], off
	v_mov_b32_e32 v67, v1
	v_lshl_add_u64 v[4:5], v[2:3], 0, v[66:67]
	v_mov_b32_e32 v69, v1
	global_load_dwordx4 v[30:33], v[4:5], off
	v_lshl_add_u64 v[4:5], v[2:3], 0, v[68:69]
	v_mov_b32_e32 v71, v1
	v_mov_b32_e32 v73, v1
	global_load_dwordx4 v[14:17], v[4:5], off
	v_lshl_add_u64 v[4:5], v[2:3], 0, v[70:71]
	v_lshl_add_u64 v[2:3], v[2:3], 0, v[72:73]
	global_load_dwordx4 v[10:13], v[4:5], off
	v_readlane_b32 s22, v254, 16
	global_load_dwordx4 v[2:5], v[2:3], off
	global_load_dwordx2 v[122:123], v[34:35], off offset:512
	global_load_dwordx2 v[124:125], v[34:35], off offset:1024
	global_load_dwordx2 v[126:127], v[34:35], off offset:1536
	global_load_dwordx2 v[128:129], v[34:35], off offset:2048
	global_load_dwordx2 v[130:131], v[34:35], off offset:2560
	global_load_dwordx2 v[132:133], v[34:35], off offset:3072
	global_load_dwordx2 v[134:135], v[34:35], off offset:3584
	v_readlane_b32 s23, v254, 17
	s_waitcnt vmcnt(11)
	v_lshlrev_b32_e32 v102, 16, v36
	v_and_b32_e32 v103, 0xffff0000, v36
	v_lshlrev_b32_e32 v104, 16, v37
	v_and_b32_e32 v105, 0xffff0000, v37
	v_mul_f32_e32 v38, v103, v103
	v_fmac_f32_e32 v38, v102, v102
	v_fmac_f32_e32 v38, v104, v104
	v_fmac_f32_e32 v38, v105, v105
	s_waitcnt vmcnt(6)
	v_and_b32_e32 v99, 0xffff0000, v122
	v_lshlrev_b32_e32 v98, 16, v122
	v_mul_f32_e32 v36, v99, v99
	v_lshlrev_b32_e32 v100, 16, v123
	v_fmac_f32_e32 v36, v98, v98
	v_and_b32_e32 v101, 0xffff0000, v123
	v_fmac_f32_e32 v36, v100, v100
	v_fmac_f32_e32 v36, v101, v101
	v_add_f32_e32 v38, v38, v36
	s_waitcnt vmcnt(5)
	v_and_b32_e32 v95, 0xffff0000, v124
	v_lshlrev_b32_e32 v94, 16, v124
	v_mul_f32_e32 v36, v95, v95
	v_lshlrev_b32_e32 v96, 16, v125
	v_fmac_f32_e32 v36, v94, v94
	v_and_b32_e32 v97, 0xffff0000, v125
	v_fmac_f32_e32 v36, v96, v96
	v_fmac_f32_e32 v36, v97, v97
	v_add_f32_e32 v38, v38, v36
	s_waitcnt vmcnt(3)
	v_lshlrev_b32_e32 v40, 16, v129
	v_and_b32_e32 v91, 0xffff0000, v126
	v_lshlrev_b32_e32 v90, 16, v126
	v_mul_f32_e32 v36, v91, v91
	v_lshlrev_b32_e32 v92, 16, v127
	v_fmac_f32_e32 v36, v90, v90
	v_and_b32_e32 v93, 0xffff0000, v127
	v_fmac_f32_e32 v36, v92, v92
	v_fmac_f32_e32 v36, v93, v93
	v_add_f32_e32 v80, v38, v36
	s_waitcnt vmcnt(2)
	v_and_b32_e32 v39, 0xffff0000, v130
	v_and_b32_e32 v38, 0xffff0000, v128
	v_lshlrev_b32_e32 v37, 16, v130
	v_lshlrev_b32_e32 v36, 16, v128
	v_and_b32_e32 v88, 0xffff0000, v129
	v_pk_mul_f32 v[76:77], v[38:39], v[38:39]
	v_lshlrev_b32_e32 v41, 16, v131
	v_pk_fma_f32 v[76:77], v[36:37], v[36:37], v[76:77]
	v_and_b32_e32 v89, 0xffff0000, v131
	v_pk_fma_f32 v[76:77], v[40:41], v[40:41], v[76:77]
	s_nop 0
	v_pk_fma_f32 v[76:77], v[88:89], v[88:89], v[76:77]
	s_nop 0
	v_add_f32_e32 v76, v80, v76
	v_add_f32_e32 v86, v76, v77
	s_nop 0
	s_waitcnt vmcnt(1)
	v_and_b32_e32 v78, 0xffff0000, v132
	s_waitcnt vmcnt(0)
	v_and_b32_e32 v79, 0xffff0000, v134
	v_lshlrev_b32_e32 v81, 16, v134
	v_lshlrev_b32_e32 v80, 16, v132
	v_lshlrev_b32_e32 v85, 16, v135
	v_and_b32_e32 v83, 0xffff0000, v135
	v_pk_mul_f32 v[34:35], v[78:79], v[78:79]
	v_lshlrev_b32_e32 v84, 16, v133
	v_pk_fma_f32 v[34:35], v[80:81], v[80:81], v[34:35]
	v_and_b32_e32 v82, 0xffff0000, v133
	v_pk_fma_f32 v[34:35], v[84:85], v[84:85], v[34:35]
	v_mul_i32_i24_e32 v76, 0x3000, v106
	v_pk_fma_f32 v[34:35], v[82:83], v[82:83], v[34:35]
	v_ashrrev_i32_e32 v77, 31, v76
	v_add_f32_e32 v34, v86, v34
	v_add_f32_e32 v34, v34, v35
	ds_bpermute_b32 v35, v87, v34
	global_load_dwordx4 v[114:117], v[44:45], off
	s_waitcnt lgkmcnt(0)
	v_add_f32_e32 v34, v34, v35
	ds_bpermute_b32 v35, v108, v34
	s_waitcnt lgkmcnt(0)
	v_add_f32_e32 v34, v34, v35
	ds_bpermute_b32 v35, v109, v34
	s_waitcnt lgkmcnt(0)
	v_add_f32_e32 v34, v34, v35
	ds_bpermute_b32 v35, v110, v34
	s_waitcnt lgkmcnt(0)
	v_add_f32_e32 v34, v34, v35
	ds_bpermute_b32 v35, v111, v34
	s_waitcnt lgkmcnt(0)
	v_add_f32_e32 v34, v34, v35
	ds_bpermute_b32 v35, v112, v34
	s_waitcnt lgkmcnt(0)
; __device__ __forceinline__ void row_pass(const RowPass& rp) {
;     ...
;             const float rstd = rsqrtf(wave_sum(ss) * (1.f / D) + EPS);
; #pragma unroll
;             for (int j = 0; j < 8; ++j) { const int col = 4 * (lane + 64 * j); const f32x4 gp = *(const f32x4*)(rp.gpost + col); const f32x4 gt = *(const f32x4*)(rp.gatev + v * 12288 + col);
;                 x[j] = x[j] + gt * (ov[j] * rstd * gp); }
;         }
;         if (rp.dst_lat) { float* xd = (row < MLAT) ? rp.dst_lat + (size_t)row * D : rp.dst_ctx + (size_t)(row - MLAT) * D;
; #pragma unroll
;             for (int j = 0; j < 8; ++j) *(f32x4*)(xd + 4 * (lane + 64 * j)) = x[j]; }
	v_add_f32_e32 v34, v34, v35
	v_fmamk_f32 v34, v34, 0x3a000000, v197
	v_cmp_gt_f32_e32 vcc, s69, v34
	v_mul_f32_e32 v35, 0x4b800000, v34
	s_nop 0
	v_cndmask_b32_e32 v34, v34, v35, vcc
	v_rsq_f32_e32 v34, v34
	s_nop 0
	v_mul_f32_e32 v35, 0x45800000, v34
	v_cndmask_b32_e32 v86, v34, v35, vcc
	v_lshl_add_u64 v[34:35], v[76:77], 2, s[10:11]
	v_lshl_add_u64 v[106:107], v[34:35], 0, v[0:1]
	global_load_dwordx4 v[118:121], v[106:107], off
	v_pk_mul_f32 v[104:105], v[104:105], v[86:87] op_sel_hi:[1,0]
	v_pk_mul_f32 v[102:103], v[102:103], v[86:87] op_sel_hi:[1,0]
	v_pk_mul_f32 v[100:101], v[100:101], v[86:87] op_sel_hi:[1,0]
	v_pk_mul_f32 v[98:99], v[98:99], v[86:87] op_sel_hi:[1,0]
	v_pk_mul_f32 v[96:97], v[96:97], v[86:87] op_sel_hi:[1,0]
	v_pk_mul_f32 v[94:95], v[94:95], v[86:87] op_sel_hi:[1,0]
	v_pk_mul_f32 v[92:93], v[92:93], v[86:87] op_sel_hi:[1,0]
	v_pk_mul_f32 v[90:91], v[90:91], v[86:87] op_sel_hi:[1,0]
	s_andn2_b64 vcc, exec, s[22:23]
	s_waitcnt vmcnt(1)
	v_pk_mul_f32 v[102:103], v[114:115], v[102:103]
	v_pk_mul_f32 v[104:105], v[116:117], v[104:105]
	s_waitcnt vmcnt(0)
	v_pk_fma_f32 v[6:7], v[118:119], v[102:103], v[6:7]
	v_pk_fma_f32 v[8:9], v[120:121], v[104:105], v[8:9]
	global_load_dwordx4 v[102:105], v[44:45], off offset:1024
	global_load_dwordx4 v[114:117], v[106:107], off offset:1024
	s_waitcnt vmcnt(1)
	v_pk_mul_f32 v[98:99], v[102:103], v[98:99]
	v_pk_mul_f32 v[100:101], v[104:105], v[100:101]
	s_waitcnt vmcnt(0)
	v_pk_fma_f32 v[18:19], v[114:115], v[98:99], v[18:19]
	v_pk_fma_f32 v[20:21], v[116:117], v[100:101], v[20:21]
	global_load_dwordx4 v[98:101], v[44:45], off offset:2048
	global_load_dwordx4 v[102:105], v[106:107], off offset:2048
	s_waitcnt vmcnt(1)
	v_pk_mul_f32 v[94:95], v[98:99], v[94:95]
	v_pk_mul_f32 v[96:97], v[100:101], v[96:97]
	s_waitcnt vmcnt(0)
	v_pk_fma_f32 v[22:23], v[102:103], v[94:95], v[22:23]
	v_pk_fma_f32 v[24:25], v[104:105], v[96:97], v[24:25]
	global_load_dwordx4 v[94:97], v[44:45], off offset:3072
	global_load_dwordx4 v[98:101], v[106:107], off offset:3072
	s_waitcnt vmcnt(1)
	v_pk_mul_f32 v[90:91], v[94:95], v[90:91]
	v_pk_mul_f32 v[92:93], v[96:97], v[92:93]
	s_waitcnt vmcnt(0)
	v_pk_fma_f32 v[26:27], v[98:99], v[90:91], v[26:27]
	v_pk_fma_f32 v[28:29], v[100:101], v[92:93], v[28:29]
	global_load_dwordx4 v[90:93], v[46:47], off
	v_lshl_add_u64 v[94:95], v[34:35], 0, v[66:67]
	global_load_dwordx4 v[94:97], v[94:95], off
	v_mov_b32_e32 v98, v40
	v_mov_b32_e32 v99, v88
	v_mov_b32_e32 v100, v36
	v_mov_b32_e32 v101, v38
	v_pk_mul_f32 v[98:99], v[98:99], v[86:87] op_sel_hi:[1,0]
	v_pk_mul_f32 v[100:101], v[100:101], v[86:87] op_sel_hi:[1,0]
	v_mov_b32_e32 v88, v41
	v_mov_b32_e32 v38, v37
	v_pk_mul_f32 v[40:41], v[88:89], v[86:87] op_sel_hi:[1,0]
	v_pk_mul_f32 v[36:37], v[38:39], v[86:87] op_sel_hi:[1,0]
	s_waitcnt vmcnt(1)
	v_pk_mul_f32 v[90:91], v[90:91], v[100:101]
	v_pk_mul_f32 v[92:93], v[92:93], v[98:99]
	s_waitcnt vmcnt(0)
	v_pk_fma_f32 v[30:31], v[94:95], v[90:91], v[30:31]
	v_pk_fma_f32 v[32:33], v[96:97], v[92:93], v[32:33]
	global_load_dwordx4 v[90:93], v[48:49], off
	v_lshl_add_u64 v[94:95], v[34:35], 0, v[68:69]
	global_load_dwordx4 v[94:97], v[94:95], off
	s_waitcnt vmcnt(1)
	v_pk_mul_f32 v[36:37], v[90:91], v[36:37]
	v_pk_mul_f32 v[38:39], v[92:93], v[40:41]
	s_waitcnt vmcnt(0)
	v_pk_fma_f32 v[14:15], v[94:95], v[36:37], v[14:15]
	v_pk_fma_f32 v[16:17], v[96:97], v[38:39], v[16:17]
	global_load_dwordx4 v[36:39], v[50:51], off
	v_lshl_add_u64 v[40:41], v[34:35], 0, v[70:71]
	global_load_dwordx4 v[88:91], v[40:41], off
	v_mov_b32_e32 v40, v84
	v_mov_b32_e32 v41, v82
	v_pk_mul_f32 v[40:41], v[40:41], v[86:87] op_sel_hi:[1,0]
	v_mov_b32_e32 v92, v80
	v_mov_b32_e32 v93, v78
	v_pk_mul_f32 v[92:93], v[92:93], v[86:87] op_sel_hi:[1,0]
	v_lshl_add_u64 v[34:35], v[34:35], 0, v[72:73]
	v_mov_b32_e32 v82, v85
	v_mov_b32_e32 v78, v81
	v_pk_mul_f32 v[82:83], v[82:83], v[86:87] op_sel_hi:[1,0]
	v_pk_mul_f32 v[78:79], v[78:79], v[86:87] op_sel_hi:[1,0]
	s_waitcnt vmcnt(1)
	v_pk_mul_f32 v[38:39], v[38:39], v[40:41]
	v_pk_mul_f32 v[36:37], v[36:37], v[92:93]
	s_waitcnt vmcnt(0)
	v_pk_fma_f32 v[12:13], v[90:91], v[38:39], v[12:13]
	global_load_dwordx4 v[38:41], v[52:53], off
	v_pk_fma_f32 v[10:11], v[88:89], v[36:37], v[10:11]
	global_load_dwordx4 v[34:37], v[34:35], off
	s_waitcnt vmcnt(1)
	v_pk_mul_f32 v[38:39], v[38:39], v[78:79]
	v_pk_mul_f32 v[40:41], v[40:41], v[82:83]
	s_waitcnt vmcnt(0)
	v_pk_fma_f32 v[2:3], v[34:35], v[38:39], v[2:3]
	v_pk_fma_f32 v[4:5], v[36:37], v[40:41], v[4:5]
	s_cbranch_vccnz .LBB0_901
	v_readlane_b32 s21, v252, 57
	v_mov_b32_e32 v35, s85
	v_mov_b32_e32 v36, s84
	v_mov_b32_e32 v34, s21
	v_readlane_b32 s21, v252, 56
	v_cndmask_b32_e64 v35, v34, v35, s[0:1]
	s_nop 0
	v_mov_b32_e32 v34, s21
	v_cndmask_b32_e64 v34, v34, v36, s[0:1]
	v_lshl_add_u64 v[34:35], v[34:35], 0, v[74:75]
	v_lshl_add_u64 v[36:37], v[34:35], 0, v[0:1]
	global_store_dwordx4 v[36:37], v[6:9], off
	global_store_dwordx4 v[36:37], v[18:21], off offset:1024
	global_store_dwordx4 v[36:37], v[22:25], off offset:2048
	global_store_dwordx4 v[36:37], v[26:29], off offset:3072
	v_lshl_add_u64 v[36:37], v[34:35], 0, v[66:67]
	global_store_dwordx4 v[36:37], v[30:33], off
	v_lshl_add_u64 v[36:37], v[34:35], 0, v[68:69]
	global_store_dwordx4 v[36:37], v[14:17], off
	v_lshl_add_u64 v[36:37], v[34:35], 0, v[70:71]
	v_lshl_add_u64 v[34:35], v[34:35], 0, v[72:73]
	global_store_dwordx4 v[36:37], v[10:13], off
	global_store_dwordx4 v[34:35], v[2:5], off
	s_branch .LBB0_901

; __device__ __forceinline__ void row_pass(const RowPass& rp) {
;     ...
;         const int v = (row < MLAT) ? (row >> 12) : 2;
;         const float* xs = (row < MLAT) ? rp.src_lat + (size_t)row * D : rp.src_ctx + (size_t)(row - MLAT) * D;
;         f32x4 x[8];
; #pragma unroll
;         for (int j = 0; j < 8; ++j) x[j] = *(const f32x4*)(xs + 4 * (lane + 64 * j));
;         if (rp.o) {
;             const bf16_t* orow = rp.o + (size_t)row * D; f32x4 ov[8]; float ss = 0.f;
; #pragma unroll
;             for (int j = 0; j < 8; ++j) { const u32x2 w2 = *(const u32x2*)(orow + 4 * (lane + 64 * j));
;                 ov[j] = (f32x4){__uint_as_float(w2.x << 16), __uint_as_float(w2.x & 0xffff0000u), __uint_as_float(w2.y << 16), __uint_as_float(w2.y & 0xffff0000u)};
;                 ss += ov[j][0] * ov[j][0] + ov[j][1] * ov[j][1] + ov[j][2] * ov[j][2] + ov[j][3] * ov[j][3]; }
;             const float rstd = rsqrtf(wave_sum(ss) * (1.f / D) + EPS);
.LBB0_1133:
	v_min_i32_e32 v0, 0x2000, v42
	v_cmp_gt_i32_e32 vcc, s70, v42
	v_ashrrev_i32_e32 v98, 12, v0
	v_add_u32_e32 v0, 0xffffe000, v42
	v_readlane_b32 s16, v252, 57
	v_cndmask_b32_e32 v2, v0, v42, vcc
	v_mov_b32_e32 v4, s85
	v_mov_b32_e32 v0, s16
	v_readlane_b32 s16, v252, 56
	v_cndmask_b32_e32 v3, 0, v43, vcc
	v_cndmask_b32_e32 v5, v0, v4, vcc
	v_mov_b32_e32 v0, s16
	v_mov_b32_e32 v4, s84
	v_cndmask_b32_e32 v4, v0, v4, vcc
	v_lshlrev_b64 v[2:3], 13, v[2:3]
	v_lshl_add_u64 v[34:35], v[78:79], 0, v[74:75]
	s_mov_b32 s16, 0x23a00000
	v_lshl_add_u64 v[2:3], v[4:5], 0, v[2:3]
	v_lshlrev_b32_e32 v0, 2, v44
	v_add_co_u32_e32 v34, vcc, s16, v34
	v_lshl_add_u64 v[88:89], v[2:3], 0, v[0:1]
	s_nop 0
	v_addc_co_u32_e32 v35, vcc, 0, v35, vcc
	global_load_dwordx4 v[6:9], v[88:89], off
	global_load_dwordx4 v[18:21], v[88:89], off offset:1024
	global_load_dwordx4 v[26:29], v[88:89], off offset:2048
	global_load_dwordx4 v[30:33], v[88:89], off offset:3072
	global_load_dwordx2 v[36:37], v[34:35], off
	v_lshlrev_b32_e32 v86, 2, v46
	v_mov_b32_e32 v87, v1
	v_lshlrev_b32_e32 v84, 2, v48
	v_mov_b32_e32 v85, v1
	v_lshlrev_b32_e32 v82, 2, v50
	v_mov_b32_e32 v83, v1
	v_lshlrev_b32_e32 v80, 2, v52
	v_mov_b32_e32 v81, v1
	v_lshl_add_u64 v[90:91], v[2:3], 0, v[86:87]
	v_lshl_add_u64 v[92:93], v[2:3], 0, v[84:85]
	v_lshl_add_u64 v[94:95], v[2:3], 0, v[82:83]
	v_lshl_add_u64 v[96:97], v[2:3], 0, v[80:81]
	global_load_dwordx4 v[22:25], v[90:91], off
	global_load_dwordx4 v[14:17], v[92:93], off
	global_load_dwordx4 v[10:13], v[94:95], off
	global_load_dwordx4 v[2:5], v[96:97], off
	global_load_dwordx2 v[138:139], v[34:35], off offset:512
	global_load_dwordx2 v[140:141], v[34:35], off offset:1024
	global_load_dwordx2 v[142:143], v[34:35], off offset:1536
	global_load_dwordx2 v[100:101], v[34:35], off offset:2048
	global_load_dwordx2 v[102:103], v[34:35], off offset:2560
	global_load_dwordx2 v[128:129], v[34:35], off offset:3072
	s_nop 0
	global_load_dwordx2 v[34:35], v[34:35], off offset:3584
	v_mul_i32_i24_e32 v98, 0x3000, v98
	v_readlane_b32 s16, v254, 16
	v_readlane_b32 s17, v254, 17
	s_waitcnt vmcnt(11)
	v_lshlrev_b32_e32 v124, 16, v36
	v_and_b32_e32 v125, 0xffff0000, v36
	v_lshlrev_b32_e32 v126, 16, v37
	v_and_b32_e32 v127, 0xffff0000, v37
	v_mul_f32_e32 v38, v125, v125
	v_fmac_f32_e32 v38, v124, v124
	v_fmac_f32_e32 v38, v126, v126
	v_fmac_f32_e32 v38, v127, v127
	s_waitcnt vmcnt(6)
	v_and_b32_e32 v121, 0xffff0000, v138
	v_lshlrev_b32_e32 v120, 16, v138
	v_mul_f32_e32 v36, v121, v121
	v_lshlrev_b32_e32 v122, 16, v139
	v_fmac_f32_e32 v36, v120, v120
	v_and_b32_e32 v123, 0xffff0000, v139
	v_fmac_f32_e32 v36, v122, v122
	v_fmac_f32_e32 v36, v123, v123
	v_add_f32_e32 v38, v38, v36
	s_waitcnt vmcnt(5)
	v_and_b32_e32 v117, 0xffff0000, v140
	v_lshlrev_b32_e32 v116, 16, v140
	v_mul_f32_e32 v36, v117, v117
	v_lshlrev_b32_e32 v118, 16, v141
	v_fmac_f32_e32 v36, v116, v116
	v_and_b32_e32 v119, 0xffff0000, v141
	v_fmac_f32_e32 v36, v118, v118
	v_fmac_f32_e32 v36, v119, v119
	v_add_f32_e32 v38, v38, v36
	s_waitcnt vmcnt(3)
	v_lshlrev_b32_e32 v40, 16, v101
	v_and_b32_e32 v113, 0xffff0000, v142
	v_lshlrev_b32_e32 v112, 16, v142
	v_mul_f32_e32 v36, v113, v113
	v_lshlrev_b32_e32 v114, 16, v143
	v_fmac_f32_e32 v36, v112, v112
	v_and_b32_e32 v115, 0xffff0000, v143
	v_fmac_f32_e32 v36, v114, v114
	v_fmac_f32_e32 v36, v115, v115
	v_add_f32_e32 v99, v38, v36
	s_waitcnt vmcnt(2)
	v_and_b32_e32 v39, 0xffff0000, v102
	v_and_b32_e32 v38, 0xffff0000, v100
	v_lshlrev_b32_e32 v37, 16, v102
	v_lshlrev_b32_e32 v36, 16, v100
	v_and_b32_e32 v110, 0xffff0000, v101
	v_pk_mul_f32 v[100:101], v[38:39], v[38:39]
	v_lshlrev_b32_e32 v41, 16, v103
	v_pk_fma_f32 v[100:101], v[36:37], v[36:37], v[100:101]
	v_and_b32_e32 v111, 0xffff0000, v103
	v_pk_fma_f32 v[100:101], v[40:41], v[40:41], v[100:101]
	s_waitcnt vmcnt(0)
	v_lshlrev_b32_e32 v103, 16, v34
	v_pk_fma_f32 v[100:101], v[110:111], v[110:111], v[100:101]
	v_lshlrev_b32_e32 v102, 16, v128
	v_add_f32_e32 v99, v99, v100
	v_add_f32_e32 v99, v99, v101
	v_and_b32_e32 v101, 0xffff0000, v34
	v_and_b32_e32 v100, 0xffff0000, v128
	v_lshlrev_b32_e32 v107, 16, v35
	v_and_b32_e32 v105, 0xffff0000, v35
	v_pk_mul_f32 v[34:35], v[100:101], v[100:101]
	v_lshlrev_b32_e32 v106, 16, v129
	v_pk_fma_f32 v[34:35], v[102:103], v[102:103], v[34:35]
	v_and_b32_e32 v104, 0xffff0000, v129
	v_pk_fma_f32 v[34:35], v[106:107], v[106:107], v[34:35]
	global_load_dwordx4 v[130:133], v[54:55], off
	v_pk_fma_f32 v[34:35], v[104:105], v[104:105], v[34:35]
	s_nop 0
	v_add_f32_e32 v34, v99, v34
	v_add_f32_e32 v34, v34, v35
	ds_bpermute_b32 v35, v45, v34
	v_ashrrev_i32_e32 v99, 31, v98
	s_waitcnt lgkmcnt(0)
	v_add_f32_e32 v34, v34, v35
	ds_bpermute_b32 v35, v47, v34
	s_waitcnt lgkmcnt(0)
	v_add_f32_e32 v34, v34, v35
	ds_bpermute_b32 v35, v49, v34
	s_waitcnt lgkmcnt(0)
	v_add_f32_e32 v34, v34, v35
	ds_bpermute_b32 v35, v51, v34
	s_waitcnt lgkmcnt(0)
	v_add_f32_e32 v34, v34, v35
	ds_bpermute_b32 v35, v53, v34
	s_waitcnt lgkmcnt(0)
	v_add_f32_e32 v34, v34, v35
	ds_bpermute_b32 v35, v109, v34
	s_waitcnt lgkmcnt(0)
; __device__ __forceinline__ void row_pass(const RowPass& rp) {
;     ...
;             const float rstd = rsqrtf(wave_sum(ss) * (1.f / D) + EPS);
; #pragma unroll
;             for (int j = 0; j < 8; ++j) { const int col = 4 * (lane + 64 * j); const f32x4 gp = *(const f32x4*)(rp.gpost + col); const f32x4 gt = *(const f32x4*)(rp.gatev + v * 12288 + col);
;                 x[j] = x[j] + gt * (ov[j] * rstd * gp); }
;         }
;         if (rp.dst_lat) { float* xd = (row < MLAT) ? rp.dst_lat + (size_t)row * D : rp.dst_ctx + (size_t)(row - MLAT) * D;
; #pragma unroll
;             for (int j = 0; j < 8; ++j) *(f32x4*)(xd + 4 * (lane + 64 * j)) = x[j]; }
	v_add_f32_e32 v34, v34, v35
	v_fmamk_f32 v34, v34, 0x3a000000, v197
	v_cmp_gt_f32_e32 vcc, s69, v34
	v_mul_f32_e32 v35, 0x4b800000, v34
	s_nop 0
	v_cndmask_b32_e32 v34, v34, v35, vcc
	v_rsq_f32_e32 v34, v34
	s_nop 0
	v_mul_f32_e32 v35, 0x45800000, v34
	v_cndmask_b32_e32 v108, v34, v35, vcc
	v_lshl_add_u64 v[34:35], v[98:99], 2, s[8:9]
	v_lshl_add_u64 v[128:129], v[34:35], 0, v[0:1]
	global_load_dwordx4 v[134:137], v[128:129], off
	v_pk_mul_f32 v[126:127], v[126:127], v[108:109] op_sel_hi:[1,0]
	v_pk_mul_f32 v[124:125], v[124:125], v[108:109] op_sel_hi:[1,0]
	v_pk_mul_f32 v[122:123], v[122:123], v[108:109] op_sel_hi:[1,0]
	v_pk_mul_f32 v[120:121], v[120:121], v[108:109] op_sel_hi:[1,0]
	v_pk_mul_f32 v[118:119], v[118:119], v[108:109] op_sel_hi:[1,0]
	v_pk_mul_f32 v[116:117], v[116:117], v[108:109] op_sel_hi:[1,0]
	v_pk_mul_f32 v[114:115], v[114:115], v[108:109] op_sel_hi:[1,0]
	v_pk_mul_f32 v[112:113], v[112:113], v[108:109] op_sel_hi:[1,0]
	s_andn2_b64 vcc, exec, s[16:17]
	s_waitcnt vmcnt(1)
	v_pk_mul_f32 v[124:125], v[130:131], v[124:125]
	v_pk_mul_f32 v[126:127], v[132:133], v[126:127]
	s_waitcnt vmcnt(0)
	v_pk_fma_f32 v[6:7], v[134:135], v[124:125], v[6:7]
	v_pk_fma_f32 v[8:9], v[136:137], v[126:127], v[8:9]
	global_load_dwordx4 v[124:127], v[54:55], off offset:1024
	global_load_dwordx4 v[130:133], v[128:129], off offset:1024
	s_waitcnt vmcnt(1)
	v_pk_mul_f32 v[120:121], v[124:125], v[120:121]
	v_pk_mul_f32 v[122:123], v[126:127], v[122:123]
	s_waitcnt vmcnt(0)
	v_pk_fma_f32 v[18:19], v[130:131], v[120:121], v[18:19]
	v_pk_fma_f32 v[20:21], v[132:133], v[122:123], v[20:21]
	global_load_dwordx4 v[120:123], v[54:55], off offset:2048
	global_load_dwordx4 v[124:127], v[128:129], off offset:2048
	s_waitcnt vmcnt(1)
	v_pk_mul_f32 v[116:117], v[120:121], v[116:117]
	v_pk_mul_f32 v[118:119], v[122:123], v[118:119]
	s_waitcnt vmcnt(0)
	v_pk_fma_f32 v[26:27], v[124:125], v[116:117], v[26:27]
	v_pk_fma_f32 v[28:29], v[126:127], v[118:119], v[28:29]
	global_load_dwordx4 v[116:119], v[54:55], off offset:3072
	global_load_dwordx4 v[120:123], v[128:129], off offset:3072
	s_waitcnt vmcnt(1)
	v_pk_mul_f32 v[112:113], v[116:117], v[112:113]
	v_pk_mul_f32 v[114:115], v[118:119], v[114:115]
	s_waitcnt vmcnt(0)
	v_pk_fma_f32 v[30:31], v[120:121], v[112:113], v[30:31]
	v_pk_fma_f32 v[32:33], v[122:123], v[114:115], v[32:33]
	global_load_dwordx4 v[112:115], v[56:57], off
	v_lshl_add_u64 v[116:117], v[34:35], 0, v[86:87]
	global_load_dwordx4 v[116:119], v[116:117], off
	v_mov_b32_e32 v120, v40
	v_mov_b32_e32 v121, v110
	v_mov_b32_e32 v122, v36
	v_mov_b32_e32 v123, v38
	v_pk_mul_f32 v[120:121], v[120:121], v[108:109] op_sel_hi:[1,0]
	v_pk_mul_f32 v[122:123], v[122:123], v[108:109] op_sel_hi:[1,0]
	v_mov_b32_e32 v110, v41
	v_mov_b32_e32 v38, v37
	v_pk_mul_f32 v[40:41], v[110:111], v[108:109] op_sel_hi:[1,0]
	v_pk_mul_f32 v[36:37], v[38:39], v[108:109] op_sel_hi:[1,0]
	s_waitcnt vmcnt(1)
	v_pk_mul_f32 v[112:113], v[112:113], v[122:123]
	v_pk_mul_f32 v[114:115], v[114:115], v[120:121]
	s_waitcnt vmcnt(0)
	v_pk_fma_f32 v[22:23], v[116:117], v[112:113], v[22:23]
	v_pk_fma_f32 v[24:25], v[118:119], v[114:115], v[24:25]
	global_load_dwordx4 v[112:115], v[58:59], off
	v_lshl_add_u64 v[116:117], v[34:35], 0, v[84:85]
	global_load_dwordx4 v[116:119], v[116:117], off
	s_waitcnt vmcnt(1)
	v_pk_mul_f32 v[36:37], v[112:113], v[36:37]
	v_pk_mul_f32 v[38:39], v[114:115], v[40:41]
	s_waitcnt vmcnt(0)
	v_pk_fma_f32 v[14:15], v[116:117], v[36:37], v[14:15]
	v_pk_fma_f32 v[16:17], v[118:119], v[38:39], v[16:17]
	global_load_dwordx4 v[36:39], v[60:61], off
	v_lshl_add_u64 v[40:41], v[34:35], 0, v[82:83]
	global_load_dwordx4 v[110:113], v[40:41], off
	v_mov_b32_e32 v40, v106
	v_mov_b32_e32 v41, v104
	v_pk_mul_f32 v[40:41], v[40:41], v[108:109] op_sel_hi:[1,0]
	v_mov_b32_e32 v114, v102
	v_mov_b32_e32 v115, v100
	v_pk_mul_f32 v[114:115], v[114:115], v[108:109] op_sel_hi:[1,0]
	v_lshl_add_u64 v[34:35], v[34:35], 0, v[80:81]
	v_mov_b32_e32 v104, v107
	v_mov_b32_e32 v100, v103
	v_pk_mul_f32 v[104:105], v[104:105], v[108:109] op_sel_hi:[1,0]
	v_pk_mul_f32 v[100:101], v[100:101], v[108:109] op_sel_hi:[1,0]
	s_waitcnt vmcnt(1)
	v_pk_mul_f32 v[38:39], v[38:39], v[40:41]
	v_pk_mul_f32 v[36:37], v[36:37], v[114:115]
	s_waitcnt vmcnt(0)
	v_pk_fma_f32 v[12:13], v[112:113], v[38:39], v[12:13]
	global_load_dwordx4 v[38:41], v[62:63], off
	v_pk_fma_f32 v[10:11], v[110:111], v[36:37], v[10:11]
	global_load_dwordx4 v[34:37], v[34:35], off
	s_waitcnt vmcnt(1)
	v_pk_mul_f32 v[38:39], v[38:39], v[100:101]
	v_pk_mul_f32 v[40:41], v[40:41], v[104:105]
	s_waitcnt vmcnt(0)
	v_pk_fma_f32 v[2:3], v[34:35], v[38:39], v[2:3]
	v_pk_fma_f32 v[4:5], v[36:37], v[40:41], v[4:5]
	s_cbranch_vccnz .LBB0_1135
	global_store_dwordx4 v[88:89], v[6:9], off
	global_store_dwordx4 v[88:89], v[18:21], off offset:1024
	global_store_dwordx4 v[88:89], v[26:29], off offset:2048
	global_store_dwordx4 v[88:89], v[30:33], off offset:3072
	global_store_dwordx4 v[90:91], v[22:25], off
	global_store_dwordx4 v[92:93], v[14:17], off
	global_store_dwordx4 v[94:95], v[10:13], off
	global_store_dwordx4 v[96:97], v[2:5], off
